# P0 transposed-weight stores (w_in^T/w_out^T tiles, W_eff fold output) write-through so barrier 1 flushes less
# speedup vs baseline: 1.0317x; 1.0018x over previous
.LBB0_16:
	s_lshl_b64 s[0:1], s[14:15], 12
	s_add_u32 s0, s42, s0
	s_addc_u32 s1, s43, s1
	s_lshl_b32 s10, s38, 1
	s_add_u32 s0, s0, s10
	s_addc_u32 s1, s1, 0
	s_add_u32 s0, s0, 0xc00000
	v_ashrrev_i32_e32 v133, 31, v132
	s_addc_u32 s1, s1, 0
	v_lshlrev_b64 v[134:135], 12, v[132:133]
	v_or_b32_e32 v146, 48, v132
	v_or_b32_e32 v148, 32, v132
	v_or_b32_e32 v132, 16, v132
	v_lshl_or_b32 v140, s35, 7, v131
	v_mov_b32_e32 v141, 0
	v_lshl_add_u64 v[134:135], s[0:1], 0, v[134:135]
	v_ashrrev_i32_e32 v147, 31, v146
	v_ashrrev_i32_e32 v149, 31, v148
	v_ashrrev_i32_e32 v133, 31, v132
	v_lshl_add_u64 v[136:137], v[134:135], 0, v[140:141]
	s_mov_b64 s[10:11], 0xb0000
	v_lshlrev_b64 v[146:147], 12, v[146:147]
	v_lshlrev_b64 v[148:149], 12, v[148:149]
	v_lshlrev_b64 v[132:133], 12, v[132:133]
	v_lshl_add_u64 v[134:135], v[136:137], 0, s[10:11]
	s_mov_b64 s[10:11], 0xa0000
	v_lshl_add_u64 v[146:147], s[0:1], 0, v[146:147]
	v_lshl_add_u64 v[148:149], s[0:1], 0, v[148:149]
	v_lshl_add_u64 v[132:133], s[0:1], 0, v[132:133]
	v_lshl_add_u64 v[138:139], v[136:137], 0, s[10:11]
	s_mov_b64 s[10:11], 0x90000
	v_lshl_add_u64 v[146:147], v[146:147], 0, v[140:141]
	v_lshl_add_u64 v[148:149], v[148:149], 0, v[140:141]
	v_lshl_add_u64 v[132:133], v[132:133], 0, v[140:141]
	s_mov_b32 s0, 0x80000
	v_lshl_add_u64 v[142:143], v[136:137], 0, s[10:11]
	s_mov_b64 s[10:11], 0x80000
	v_cvt_pk_bf16_f32 v122, v122, v123
	v_cvt_pk_bf16_f32 v123, v124, v125
	v_cvt_pk_bf16_f32 v124, v114, v115
	v_cvt_pk_bf16_f32 v125, v116, v117
	global_store_dwordx4 v[136:137], v[122:125], off sc0 sc1
	v_cvt_pk_bf16_f32 v114, v126, v127
	v_cvt_pk_bf16_f32 v115, v128, v129
	v_cvt_pk_bf16_f32 v116, v118, v119
	v_cvt_pk_bf16_f32 v117, v120, v121
	global_store_dwordx4 v[136:137], v[114:117], off offset:64 sc0 sc1
	v_cvt_pk_bf16_f32 v106, v106, v107
	v_cvt_pk_bf16_f32 v107, v108, v109
	v_cvt_pk_bf16_f32 v108, v98, v99
	v_cvt_pk_bf16_f32 v109, v100, v101
	global_store_dwordx4 v[132:133], v[106:109], off sc0 sc1
	v_cvt_pk_bf16_f32 v98, v110, v111
	v_cvt_pk_bf16_f32 v99, v112, v113
	v_cvt_pk_bf16_f32 v100, v102, v103
	v_cvt_pk_bf16_f32 v101, v104, v105
	global_store_dwordx4 v[132:133], v[98:101], off offset:64 sc0 sc1
	v_cvt_pk_bf16_f32 v90, v90, v91
	v_cvt_pk_bf16_f32 v91, v92, v93
	v_cvt_pk_bf16_f32 v92, v82, v83
	v_cvt_pk_bf16_f32 v93, v84, v85
	global_store_dwordx4 v[148:149], v[90:93], off sc0 sc1
	v_cvt_pk_bf16_f32 v82, v94, v95
	v_cvt_pk_bf16_f32 v83, v96, v97
	v_cvt_pk_bf16_f32 v84, v86, v87
	v_cvt_pk_bf16_f32 v85, v88, v89
	global_store_dwordx4 v[148:149], v[82:85], off offset:64 sc0 sc1
	v_cvt_pk_bf16_f32 v58, v58, v59
	v_cvt_pk_bf16_f32 v59, v60, v61
	v_cvt_pk_bf16_f32 v60, v50, v51
	v_cvt_pk_bf16_f32 v61, v52, v53
	global_store_dwordx4 v[146:147], v[58:61], off sc0 sc1
	v_cvt_pk_bf16_f32 v50, v62, v63
	v_cvt_pk_bf16_f32 v51, v64, v65
	v_cvt_pk_bf16_f32 v52, v54, v55
	v_cvt_pk_bf16_f32 v53, v56, v57
	v_add_co_u32_e32 v54, vcc, s0, v136
	v_lshl_add_u64 v[144:145], v[136:137], 0, s[10:11]
	global_store_dwordx4 v[146:147], v[50:53], off offset:64 sc0 sc1
	v_addc_co_u32_e32 v55, vcc, 0, v137, vcc
	s_nop 0
	v_cvt_pk_bf16_f32 v50, v78, v79
	v_cvt_pk_bf16_f32 v51, v80, v81
	v_cvt_pk_bf16_f32 v52, v70, v71
	v_cvt_pk_bf16_f32 v53, v72, v73
	s_mov_b32 s0, 0x90000
	global_store_dwordx4 v[54:55], v[50:53], off sc0 sc1
	s_nop 1
	v_cvt_pk_bf16_f32 v50, v74, v75
	v_cvt_pk_bf16_f32 v51, v76, v77
	v_cvt_pk_bf16_f32 v52, v66, v67
	v_cvt_pk_bf16_f32 v53, v68, v69
	global_store_dwordx4 v[144:145], v[50:53], off offset:64 sc0 sc1
	v_cvt_pk_bf16_f32 v46, v46, v47
	v_cvt_pk_bf16_f32 v47, v48, v49
	v_cvt_pk_bf16_f32 v48, v38, v39
	v_add_co_u32_e32 v38, vcc, s0, v136
	s_mov_b32 s0, 0xa0000
	s_nop 0
	v_addc_co_u32_e32 v39, vcc, 0, v137, vcc
	v_cvt_pk_bf16_f32 v49, v40, v41
	global_store_dwordx4 v[38:39], v[46:49], off sc0 sc1
	v_cvt_pk_bf16_f32 v38, v42, v43
	v_cvt_pk_bf16_f32 v39, v44, v45
	v_cvt_pk_bf16_f32 v40, v34, v35
	v_cvt_pk_bf16_f32 v41, v36, v37
	global_store_dwordx4 v[142:143], v[38:41], off offset:64 sc0 sc1
	v_cvt_pk_bf16_f32 v30, v30, v31
	v_cvt_pk_bf16_f32 v31, v32, v33
	v_cvt_pk_bf16_f32 v32, v22, v23
	v_add_co_u32_e32 v22, vcc, s0, v136
	s_mov_b32 s0, 0xb0000
	s_nop 0
	v_addc_co_u32_e32 v23, vcc, 0, v137, vcc
	v_cvt_pk_bf16_f32 v33, v24, v25
	global_store_dwordx4 v[22:23], v[30:33], off sc0 sc1
	v_cvt_pk_bf16_f32 v22, v26, v27
	v_cvt_pk_bf16_f32 v23, v28, v29
	v_cvt_pk_bf16_f32 v24, v18, v19
	v_cvt_pk_bf16_f32 v25, v20, v21
	global_store_dwordx4 v[138:139], v[22:25], off offset:64 sc0 sc1
	v_cvt_pk_bf16_f32 v14, v14, v15
	v_cvt_pk_bf16_f32 v15, v16, v17
	v_cvt_pk_bf16_f32 v16, v6, v7
	v_add_co_u32_e32 v6, vcc, s0, v136
	v_cvt_pk_bf16_f32 v17, v8, v9
	s_nop 1
	v_addc_co_u32_e32 v7, vcc, 0, v137, vcc
	global_store_dwordx4 v[6:7], v[14:17], off sc0 sc1
	v_cvt_pk_bf16_f32 v6, v10, v11
	v_cvt_pk_bf16_f32 v7, v12, v13
	v_cvt_pk_bf16_f32 v8, v2, v3
	v_cvt_pk_bf16_f32 v9, v4, v5
	global_store_dwordx4 v[134:135], v[6:9], off offset:64 sc0 sc1
	s_waitcnt vmcnt(0)
	s_barrier

.LBB0_36:
	s_add_u32 s34, s64, s6
	s_addc_u32 s37, s65, s7
	s_and_b64 s[0:1], s[0:1], exec
	s_movk_i32 s0, 0x1800
	s_cselect_b32 s19, s19, s25
	s_cselect_b32 s25, s0, 0x800
	v_readlane_b32 s0, v254, 9
	v_readlane_b32 s1, v254, 10
	s_cselect_b32 s24, s18, s24
	s_cselect_b32 s9, s43, s1
	s_cselect_b32 s18, s42, s0
	s_lshr_b32 s0, s25, 6
	v_cvt_f32_ubyte0_e32 v2, s0
	v_rcp_iflag_f32_e32 v2, v2
	s_sub_i32 s7, 0, s0
	s_abs_i32 s6, s8
	s_ashr_i32 s1, s8, 31
	v_mul_f32_e32 v2, 0x4f7ffffe, v2
	v_cvt_u32_f32_e32 v2, v2
	v_lshrrev_b32_e32 v128, 4, v1
	v_mov_b32_e32 v67, 0
	v_readfirstlane_b32 s14, v2
	s_mul_i32 s7, s7, s14
	s_mul_hi_u32 s7, s14, s7
	s_add_i32 s14, s14, s7
	s_mul_hi_u32 s7, s6, s14
	s_mul_i32 s14, s7, s0
	s_sub_i32 s6, s6, s14
	s_add_i32 s14, s7, 1
	s_sub_i32 s39, s6, s0
	s_cmp_ge_u32 s6, s0
	s_cselect_b32 s7, s14, s7
	s_cselect_b32 s6, s39, s6
	s_add_i32 s14, s7, 1
	s_cmp_ge_u32 s6, s0
	s_cselect_b32 s6, s14, s7
	s_lshr_b32 s39, s15, 6
	v_cvt_f32_ubyte0_e32 v2, s39
	v_rcp_iflag_f32_e32 v2, v2
	s_xor_b32 s6, s6, s1
	s_sub_i32 s1, s6, s1
	s_mul_i32 s0, s1, s0
	v_mul_f32_e32 v2, 0x4f7ffffe, v2
	v_cvt_u32_f32_e32 v2, v2
	s_sub_i32 s0, s8, s0
	s_sub_i32 s7, 0, s39
	s_abs_i32 s6, s38
	v_readfirstlane_b32 s8, v2
	s_mul_i32 s7, s7, s8
	s_mul_hi_u32 s7, s8, s7
	s_add_i32 s8, s8, s7
	s_mul_hi_u32 s7, s6, s8
	s_mul_i32 s8, s7, s39
	s_sub_i32 s6, s6, s8
	s_lshl_b32 s14, s1, 6
	s_lshl_b32 s0, s0, 6
	s_ashr_i32 s1, s38, 31
	s_add_i32 s8, s7, 1
	s_sub_i32 s40, s6, s39
	s_cmp_ge_u32 s6, s39
	s_cselect_b32 s7, s8, s7
	s_cselect_b32 s6, s40, s6
	s_add_i32 s8, s7, 1
	s_cmp_ge_u32 s6, s39
	s_cselect_b32 s6, s8, s7
	s_xor_b32 s6, s6, s1
	s_sub_i32 s40, s6, s1
	s_ashr_i32 s1, s0, 31
	s_lshl_b32 s8, s40, 6
	s_lshl_b64 s[6:7], s[0:1], 2
	s_add_u32 s6, s24, s6
	v_lshlrev_b32_e32 v2, 4, v1
	v_or_b32_e32 v8, s14, v128
	s_addc_u32 s7, s19, s7
	v_and_b32_e32 v66, 0xf0, v2
	v_lshl_add_u64 v[2:3], s[6:7], 0, v[66:67]
	v_mad_i64_i32 v[4:5], s[6:7], v8, s25, 0
	v_or_b32_e32 v6, 4, v8
	v_lshl_add_u64 v[4:5], v[4:5], 2, v[2:3]
	v_mad_i64_i32 v[6:7], s[6:7], v6, s25, 0
	v_lshl_add_u64 v[6:7], v[6:7], 2, v[2:3]
	global_load_dwordx4 v[68:71], v[4:5], off nt
	global_load_dwordx4 v[72:75], v[6:7], off nt
	v_or_b32_e32 v4, 8, v8
	v_mad_i64_i32 v[4:5], s[6:7], v4, s25, 0
	v_or_b32_e32 v6, 12, v8
	v_lshl_add_u64 v[4:5], v[4:5], 2, v[2:3]
	v_mad_i64_i32 v[6:7], s[6:7], v6, s25, 0
	v_lshl_add_u64 v[6:7], v[6:7], 2, v[2:3]
	global_load_dwordx4 v[76:79], v[4:5], off nt
	global_load_dwordx4 v[80:83], v[6:7], off nt
	v_or_b32_e32 v4, 16, v8
	v_mad_i64_i32 v[4:5], s[6:7], v4, s25, 0
	v_or_b32_e32 v6, 20, v8
	v_lshl_add_u64 v[4:5], v[4:5], 2, v[2:3]
	v_mad_i64_i32 v[6:7], s[6:7], v6, s25, 0
	v_lshl_add_u64 v[6:7], v[6:7], 2, v[2:3]
	global_load_dwordx4 v[84:87], v[4:5], off nt
	global_load_dwordx4 v[88:91], v[6:7], off nt
	v_or_b32_e32 v4, 24, v8
	v_mad_i64_i32 v[4:5], s[6:7], v4, s25, 0
	v_or_b32_e32 v6, 28, v8
	v_lshl_add_u64 v[4:5], v[4:5], 2, v[2:3]
	v_mad_i64_i32 v[6:7], s[6:7], v6, s25, 0
	v_lshl_add_u64 v[6:7], v[6:7], 2, v[2:3]
	global_load_dwordx4 v[92:95], v[4:5], off nt
	global_load_dwordx4 v[96:99], v[6:7], off nt
	v_or_b32_e32 v4, 32, v8
	v_mad_i64_i32 v[4:5], s[6:7], v4, s25, 0
	v_or_b32_e32 v6, 36, v8
	v_lshl_add_u64 v[4:5], v[4:5], 2, v[2:3]
	v_mad_i64_i32 v[6:7], s[6:7], v6, s25, 0
	v_lshl_add_u64 v[6:7], v[6:7], 2, v[2:3]
	global_load_dwordx4 v[100:103], v[4:5], off nt
	global_load_dwordx4 v[104:107], v[6:7], off nt
	v_or_b32_e32 v4, 40, v8
	v_mad_i64_i32 v[4:5], s[6:7], v4, s25, 0
	v_or_b32_e32 v6, 44, v8
	v_lshl_add_u64 v[4:5], v[4:5], 2, v[2:3]
	v_mad_i64_i32 v[6:7], s[6:7], v6, s25, 0
	v_lshl_add_u64 v[6:7], v[6:7], 2, v[2:3]
	global_load_dwordx4 v[108:111], v[4:5], off nt
	global_load_dwordx4 v[112:115], v[6:7], off nt
	v_or_b32_e32 v4, 48, v8
	v_mad_i64_i32 v[4:5], s[6:7], v4, s25, 0
	v_or_b32_e32 v6, 52, v8
	v_lshl_add_u64 v[4:5], v[4:5], 2, v[2:3]
	v_mad_i64_i32 v[6:7], s[6:7], v6, s25, 0
	v_lshl_add_u64 v[6:7], v[6:7], 2, v[2:3]
	global_load_dwordx4 v[116:119], v[4:5], off nt
	global_load_dwordx4 v[120:123], v[6:7], off nt
	v_or_b32_e32 v4, 56, v8
	v_mad_i64_i32 v[4:5], s[6:7], v4, s25, 0
	v_or_b32_e32 v6, 60, v8
	v_lshl_add_u64 v[4:5], v[4:5], 2, v[2:3]
	v_mad_i64_i32 v[6:7], s[6:7], v6, s25, 0
	v_lshl_add_u64 v[2:3], v[6:7], 2, v[2:3]
	global_load_dwordx4 v[124:127], v[4:5], off nt
	global_load_dwordx4 v[132:135], v[2:3], off nt
	s_mul_i32 s40, s40, s39
	s_sub_i32 s1, s38, s40
	s_lshl_b32 s6, s1, 6
	s_ashr_i32 s7, s6, 31
	s_lshl_b64 s[24:25], s[6:7], 2
	v_or_b32_e32 v62, s8, v128
	s_add_u32 s20, s20, s24
	s_addc_u32 s21, s21, s25
	v_or_b32_e32 v10, 8, v62
	v_lshl_add_u64 v[58:59], s[20:21], 0, v[66:67]
	v_or_b32_e32 v4, 4, v62
	v_mad_i64_i32 v[10:11], s[20:21], v10, s15, 0
	v_mad_i64_i32 v[2:3], s[20:21], v62, s15, 0
	v_mad_i64_i32 v[4:5], s[20:21], v4, s15, 0
	v_lshl_add_u64 v[18:19], v[10:11], 2, v[58:59]
	v_or_b32_e32 v10, 12, v62
	v_lshl_add_u64 v[2:3], v[2:3], 2, v[58:59]
	v_lshl_add_u64 v[4:5], v[4:5], 2, v[58:59]
	v_mad_i64_i32 v[10:11], s[20:21], v10, s15, 0
	global_load_dwordx4 v[6:9], v[2:3], off nt
	s_nop 0
	global_load_dwordx4 v[2:5], v[4:5], off nt
	v_lshl_add_u64 v[20:21], v[10:11], 2, v[58:59]
	global_load_dwordx4 v[14:17], v[18:19], off nt
	global_load_dwordx4 v[10:13], v[20:21], off nt
	v_or_b32_e32 v18, 16, v62
	v_mad_i64_i32 v[18:19], s[20:21], v18, s15, 0
	v_lshl_add_u64 v[26:27], v[18:19], 2, v[58:59]
	v_or_b32_e32 v18, 20, v62
	v_mad_i64_i32 v[18:19], s[20:21], v18, s15, 0
	v_lshl_add_u64 v[28:29], v[18:19], 2, v[58:59]
	global_load_dwordx4 v[22:25], v[26:27], off nt
	global_load_dwordx4 v[18:21], v[28:29], off nt
	v_or_b32_e32 v26, 24, v62
	v_mad_i64_i32 v[26:27], s[20:21], v26, s15, 0
	v_lshl_add_u64 v[34:35], v[26:27], 2, v[58:59]
	v_or_b32_e32 v26, 28, v62
	v_mad_i64_i32 v[26:27], s[20:21], v26, s15, 0
	v_lshl_add_u64 v[36:37], v[26:27], 2, v[58:59]
	global_load_dwordx4 v[30:33], v[34:35], off nt
	global_load_dwordx4 v[26:29], v[36:37], off nt
	v_or_b32_e32 v34, 32, v62
	v_mad_i64_i32 v[34:35], s[20:21], v34, s15, 0
	v_lshl_add_u64 v[42:43], v[34:35], 2, v[58:59]
	v_or_b32_e32 v34, 36, v62
	v_mad_i64_i32 v[34:35], s[20:21], v34, s15, 0
	v_lshl_add_u64 v[44:45], v[34:35], 2, v[58:59]
	global_load_dwordx4 v[38:41], v[42:43], off nt
	global_load_dwordx4 v[34:37], v[44:45], off nt
	v_or_b32_e32 v42, 40, v62
	v_mad_i64_i32 v[42:43], s[20:21], v42, s15, 0
	v_lshl_add_u64 v[50:51], v[42:43], 2, v[58:59]
	v_or_b32_e32 v42, 44, v62
	v_mad_i64_i32 v[42:43], s[20:21], v42, s15, 0
	v_lshl_add_u64 v[52:53], v[42:43], 2, v[58:59]
	global_load_dwordx4 v[46:49], v[50:51], off nt
	global_load_dwordx4 v[42:45], v[52:53], off nt
	v_or_b32_e32 v50, 48, v62
	v_or_b32_e32 v52, 52, v62
	v_or_b32_e32 v60, 56, v62
	v_or_b32_e32 v62, 60, v62
	v_mad_i64_i32 v[50:51], s[20:21], v50, s15, 0
	v_mad_i64_i32 v[52:53], s[20:21], v52, s15, 0
	v_mad_i64_i32 v[60:61], s[20:21], v60, s15, 0
	v_mad_i64_i32 v[62:63], s[20:21], v62, s15, 0
	v_lshl_add_u64 v[50:51], v[50:51], 2, v[58:59]
	v_lshl_add_u64 v[52:53], v[52:53], 2, v[58:59]
	v_lshl_add_u64 v[60:61], v[60:61], 2, v[58:59]
	v_lshl_add_u64 v[58:59], v[62:63], 2, v[58:59]
	global_load_dwordx4 v[54:57], v[50:51], off nt
	s_nop 0
	global_load_dwordx4 v[50:53], v[52:53], off nt
	s_nop 0
	global_load_dwordx4 v[62:65], v[60:61], off nt
	s_nop 0
	global_load_dwordx4 v[58:61], v[58:59], off nt
	v_mul_u32_u24_e32 v128, 0x104, v128
	v_add3_u32 v128, s3, v66, v128
	v_add_u32_e32 v138, 0xc30, v128
	s_waitcnt vmcnt(0)
	ds_write2_b32 v128, v68, v69 offset1:1
	ds_write2_b32 v128, v70, v71 offset0:2 offset1:3
	ds_write2_b32 v138, v80, v81 offset1:1
	v_add_u32_e32 v80, 0xc38, v128
	v_add_u32_e32 v81, 0x1040, v128
	ds_write2_b32 v80, v82, v83 offset1:1
	ds_write2_b32 v81, v84, v85 offset1:1
	v_add_u32_e32 v82, 0x1048, v128
	v_add_u32_e32 v83, 0x1450, v128
	v_add_u32_e32 v84, 0x1458, v128
	ds_write2_b32 v82, v86, v87 offset1:1
	ds_write2_b32 v83, v88, v89 offset1:1
	ds_write2_b32 v84, v90, v91 offset1:1
	v_add_u32_e32 v85, 0x1860, v128
	v_add_u32_e32 v86, 0x1868, v128
	v_add_u32_e32 v87, 0x1c70, v128
	v_add_u32_e32 v88, 0x1c78, v128
	v_add_u32_e32 v89, 0x2080, v128
	v_add_u32_e32 v90, 0x2088, v128
	v_add_u32_e32 v91, 0x2490, v128
	v_add_u32_e32 v129, 0x410, v128
	v_add_u32_e32 v131, 0x418, v128
	v_add_u32_e32 v136, 0x820, v128
	v_add_u32_e32 v137, 0x828, v128
	ds_write2_b32 v85, v92, v93 offset1:1
	ds_write2_b32 v86, v94, v95 offset1:1
	ds_write2_b32 v87, v96, v97 offset1:1
	ds_write2_b32 v88, v98, v99 offset1:1
	ds_write2_b32 v89, v100, v101 offset1:1
	ds_write2_b32 v90, v102, v103 offset1:1
	ds_write2_b32 v91, v104, v105 offset1:1
	v_add_u32_e32 v92, 0x2498, v128
	v_add_u32_e32 v93, 0x28a0, v128
	v_add_u32_e32 v94, 0x28a8, v128
	v_add_u32_e32 v95, 0x2cb0, v128
	v_add_u32_e32 v96, 0x2cb8, v128
	v_add_u32_e32 v97, 0x30c0, v128
	v_add_u32_e32 v98, 0x30c8, v128
	v_add_u32_e32 v99, 0x34d0, v128
	v_add_u32_e32 v100, 0x34d8, v128
	v_add_u32_e32 v101, 0x38e0, v128
	v_add_u32_e32 v102, 0x38e8, v128
	v_add_u32_e32 v103, 0x3cf0, v128
	v_add_u32_e32 v104, 0x3cf8, v128
	ds_write2_b32 v129, v72, v73 offset1:1
	ds_write2_b32 v131, v74, v75 offset1:1
	ds_write2_b32 v136, v76, v77 offset1:1
	ds_write2_b32 v137, v78, v79 offset1:1
	ds_write2_b32 v92, v106, v107 offset1:1
	ds_write2_b32 v93, v108, v109 offset1:1
	ds_write2_b32 v94, v110, v111 offset1:1
	ds_write2_b32 v95, v112, v113 offset1:1
	ds_write2_b32 v96, v114, v115 offset1:1
	ds_write2_b32 v97, v116, v117 offset1:1
	ds_write2_b32 v98, v118, v119 offset1:1
	ds_write2_b32 v99, v120, v121 offset1:1
	ds_write2_b32 v100, v122, v123 offset1:1
	ds_write2_b32 v101, v124, v125 offset1:1
	ds_write2_b32 v102, v126, v127 offset1:1
	ds_write2_b32 v103, v132, v133 offset1:1
	ds_write2_b32 v104, v134, v135 offset1:1
	v_and_b32_e32 v66, 7, v130
	v_lshrrev_b32_e32 v105, 3, v1
	s_waitcnt lgkmcnt(0)
	v_mul_u32_u24_e32 v1, 0x820, v66
	v_lshlrev_b32_e32 v68, 2, v105
	v_add3_u32 v1, s3, v1, v68
	ds_read2_b32 v[68:69], v1 offset1:65
	s_waitcnt lgkmcnt(0)
	v_cvt_pk_bf16_f32 v70, v68, v69
	ds_read2_b32 v[68:69], v1 offset0:130 offset1:195
	s_waitcnt lgkmcnt(0)
	v_cvt_pk_bf16_f32 v71, v68, v69
	v_add_u32_e32 v68, 0x400, v1
	ds_read2_b32 v[72:73], v68 offset0:4 offset1:69
	s_ashr_i32 s15, s14, 31
	s_lshl_b64 s[14:15], s[14:15], 1
	s_waitcnt lgkmcnt(0)
	v_cvt_pk_bf16_f32 v72, v72, v73
	ds_read2_b32 v[74:75], v68 offset0:134 offset1:199
	s_add_u32 s14, s18, s14
	s_waitcnt lgkmcnt(0)
	v_cvt_pk_bf16_f32 v73, v74, v75
	v_or_b32_e32 v74, s0, v105
	s_addc_u32 s15, s9, s15
	v_lshlrev_b32_e32 v66, 4, v66
	v_ashrrev_i32_e32 v75, 31, v74
	v_lshl_add_u64 v[76:77], s[14:15], 0, v[66:67]
	v_lshlrev_b64 v[74:75], 12, v[74:75]
	v_lshl_add_u64 v[74:75], v[76:77], 0, v[74:75]
	ds_read2_b32 v[78:79], v1 offset0:8 offset1:73
	global_store_dwordx4 v[74:75], v[70:73], off sc0 sc1
	v_or_b32_e32 v69, 8, v105
	v_or_b32_e32 v106, 16, v105
	s_waitcnt lgkmcnt(0)
	v_cvt_pk_bf16_f32 v70, v78, v79
	ds_read2_b32 v[72:73], v1 offset0:138 offset1:203
	s_waitcnt lgkmcnt(0)
	v_cvt_pk_bf16_f32 v71, v72, v73
	ds_read2_b32 v[72:73], v68 offset0:12 offset1:77
	s_waitcnt lgkmcnt(0)
	v_cvt_pk_bf16_f32 v72, v72, v73
	ds_read2_b32 v[74:75], v68 offset0:142 offset1:207
	s_waitcnt lgkmcnt(0)
	v_cvt_pk_bf16_f32 v73, v74, v75
	v_or_b32_e32 v74, s0, v69
	v_ashrrev_i32_e32 v75, 31, v74
	v_lshlrev_b64 v[74:75], 12, v[74:75]
	v_lshl_add_u64 v[74:75], v[76:77], 0, v[74:75]
	ds_read2_b32 v[78:79], v1 offset0:16 offset1:81
	global_store_dwordx4 v[74:75], v[70:73], off sc0 sc1
	v_or_b32_e32 v107, 24, v105
	v_or_b32_e32 v108, 32, v105
	s_waitcnt lgkmcnt(0)
	v_cvt_pk_bf16_f32 v70, v78, v79
	ds_read2_b32 v[72:73], v1 offset0:146 offset1:211
	s_waitcnt lgkmcnt(0)
	v_cvt_pk_bf16_f32 v71, v72, v73
	ds_read2_b32 v[72:73], v68 offset0:20 offset1:85
	s_waitcnt lgkmcnt(0)
	v_cvt_pk_bf16_f32 v72, v72, v73
	ds_read2_b32 v[74:75], v68 offset0:150 offset1:215
	s_waitcnt lgkmcnt(0)
	v_cvt_pk_bf16_f32 v73, v74, v75
	v_or_b32_e32 v74, s0, v106
	v_ashrrev_i32_e32 v75, 31, v74
	v_lshlrev_b64 v[74:75], 12, v[74:75]
	v_lshl_add_u64 v[74:75], v[76:77], 0, v[74:75]
	ds_read2_b32 v[78:79], v1 offset0:24 offset1:89
	global_store_dwordx4 v[74:75], v[70:73], off sc0 sc1
	v_or_b32_e32 v109, 40, v105
	v_or_b32_e32 v110, 48, v105
	s_waitcnt lgkmcnt(0)
	v_cvt_pk_bf16_f32 v70, v78, v79
	ds_read2_b32 v[72:73], v1 offset0:154 offset1:219
	s_waitcnt lgkmcnt(0)
	v_cvt_pk_bf16_f32 v71, v72, v73
	ds_read2_b32 v[72:73], v68 offset0:28 offset1:93
	s_waitcnt lgkmcnt(0)
	v_cvt_pk_bf16_f32 v72, v72, v73
	ds_read2_b32 v[74:75], v68 offset0:158 offset1:223
	s_waitcnt lgkmcnt(0)
	v_cvt_pk_bf16_f32 v73, v74, v75
	v_or_b32_e32 v74, s0, v107
	v_ashrrev_i32_e32 v75, 31, v74
	v_lshlrev_b64 v[74:75], 12, v[74:75]
	v_lshl_add_u64 v[74:75], v[76:77], 0, v[74:75]
	ds_read2_b32 v[78:79], v1 offset0:32 offset1:97
	global_store_dwordx4 v[74:75], v[70:73], off sc0 sc1
	s_ashr_i32 s9, s8, 31
	s_waitcnt lgkmcnt(0)
	v_cvt_pk_bf16_f32 v70, v78, v79
	ds_read2_b32 v[72:73], v1 offset0:162 offset1:227
	s_waitcnt lgkmcnt(0)
	v_cvt_pk_bf16_f32 v71, v72, v73
	ds_read2_b32 v[72:73], v68 offset0:36 offset1:101
	s_waitcnt lgkmcnt(0)
	v_cvt_pk_bf16_f32 v72, v72, v73
	ds_read2_b32 v[74:75], v68 offset0:166 offset1:231
	s_waitcnt lgkmcnt(0)
	v_cvt_pk_bf16_f32 v73, v74, v75
	v_or_b32_e32 v74, s0, v108
	v_ashrrev_i32_e32 v75, 31, v74
	v_lshlrev_b64 v[74:75], 12, v[74:75]
	v_lshl_add_u64 v[74:75], v[76:77], 0, v[74:75]
	ds_read2_b32 v[78:79], v1 offset0:40 offset1:105
	global_store_dwordx4 v[74:75], v[70:73], off sc0 sc1
	s_waitcnt lgkmcnt(0)
	s_nop 0
	v_cvt_pk_bf16_f32 v70, v78, v79
	ds_read2_b32 v[72:73], v1 offset0:170 offset1:235
	s_waitcnt lgkmcnt(0)
	v_cvt_pk_bf16_f32 v71, v72, v73
	ds_read2_b32 v[72:73], v68 offset0:44 offset1:109
	s_waitcnt lgkmcnt(0)
	v_cvt_pk_bf16_f32 v72, v72, v73
	ds_read2_b32 v[74:75], v68 offset0:174 offset1:239
	s_waitcnt lgkmcnt(0)
	v_cvt_pk_bf16_f32 v73, v74, v75
	v_or_b32_e32 v74, s0, v109
	v_ashrrev_i32_e32 v75, 31, v74
	v_lshlrev_b64 v[74:75], 12, v[74:75]
	v_lshl_add_u64 v[74:75], v[76:77], 0, v[74:75]
	ds_read2_b32 v[78:79], v1 offset0:48 offset1:113
	global_store_dwordx4 v[74:75], v[70:73], off sc0 sc1
	s_waitcnt lgkmcnt(0)
	s_nop 0
	v_cvt_pk_bf16_f32 v70, v78, v79
	ds_read2_b32 v[72:73], v1 offset0:178 offset1:243
	s_waitcnt lgkmcnt(0)
	v_cvt_pk_bf16_f32 v71, v72, v73
	ds_read2_b32 v[72:73], v68 offset0:52 offset1:117
	s_waitcnt lgkmcnt(0)
	v_cvt_pk_bf16_f32 v72, v72, v73
	ds_read2_b32 v[74:75], v68 offset0:182 offset1:247
	s_waitcnt lgkmcnt(0)
	v_cvt_pk_bf16_f32 v73, v74, v75
	v_or_b32_e32 v74, s0, v110
	v_ashrrev_i32_e32 v75, 31, v74
	v_lshlrev_b64 v[74:75], 12, v[74:75]
	v_lshl_add_u64 v[74:75], v[76:77], 0, v[74:75]
	ds_read2_b32 v[78:79], v1 offset0:56 offset1:121
	global_store_dwordx4 v[74:75], v[70:73], off sc0 sc1
	s_waitcnt lgkmcnt(0)
	s_nop 0
	v_cvt_pk_bf16_f32 v70, v78, v79
	ds_read2_b32 v[72:73], v1 offset0:186 offset1:251
	s_waitcnt lgkmcnt(0)
	v_cvt_pk_bf16_f32 v71, v72, v73
	ds_read2_b32 v[72:73], v68 offset0:60 offset1:125
	s_waitcnt lgkmcnt(0)
	v_cvt_pk_bf16_f32 v72, v72, v73
	ds_read2_b32 v[74:75], v68 offset0:190 offset1:255
	v_or_b32_e32 v78, 56, v105
	s_waitcnt lgkmcnt(0)
	v_cvt_pk_bf16_f32 v73, v74, v75
	v_or_b32_e32 v74, s0, v78
	v_ashrrev_i32_e32 v75, 31, v74
	v_lshlrev_b64 v[74:75], 12, v[74:75]
	v_lshl_add_u64 v[74:75], v[76:77], 0, v[74:75]
	global_store_dwordx4 v[74:75], v[70:73], off sc0 sc1
	s_waitcnt lgkmcnt(0)
	ds_write2_b32 v128, v6, v7 offset1:1
	ds_write2_b32 v128, v8, v9 offset0:2 offset1:3
	ds_write2_b32 v129, v2, v3 offset1:1
	ds_write2_b32 v131, v4, v5 offset1:1
	ds_write2_b32 v136, v14, v15 offset1:1
	ds_write2_b32 v137, v16, v17 offset1:1
	ds_write2_b32 v138, v10, v11 offset1:1
	ds_write2_b32 v80, v12, v13 offset1:1
	ds_write2_b32 v81, v22, v23 offset1:1
	ds_write2_b32 v82, v24, v25 offset1:1
	ds_write2_b32 v83, v18, v19 offset1:1
	ds_write2_b32 v84, v20, v21 offset1:1
	ds_write2_b32 v85, v30, v31 offset1:1
	ds_write2_b32 v86, v32, v33 offset1:1
	ds_write2_b32 v87, v26, v27 offset1:1
	ds_write2_b32 v88, v28, v29 offset1:1
	ds_write2_b32 v89, v38, v39 offset1:1
	ds_write2_b32 v90, v40, v41 offset1:1
	ds_write2_b32 v91, v34, v35 offset1:1
	ds_write2_b32 v92, v36, v37 offset1:1
	ds_write2_b32 v93, v46, v47 offset1:1
	ds_write2_b32 v94, v48, v49 offset1:1
	ds_write2_b32 v95, v42, v43 offset1:1
	ds_write2_b32 v96, v44, v45 offset1:1
	ds_write2_b32 v97, v54, v55 offset1:1
	ds_write2_b32 v98, v56, v57 offset1:1
	ds_write2_b32 v99, v50, v51 offset1:1
	ds_write2_b32 v100, v52, v53 offset1:1
	ds_write2_b32 v101, v62, v63 offset1:1
	ds_write2_b32 v102, v64, v65 offset1:1
	ds_write2_b32 v103, v58, v59 offset1:1
	ds_write2_b32 v104, v60, v61 offset1:1
	s_waitcnt lgkmcnt(0)
	ds_read2_b32 v[2:3], v1 offset1:65
	s_waitcnt lgkmcnt(0)
	v_cvt_pk_bf16_f32 v2, v2, v3
	ds_read2_b32 v[4:5], v1 offset0:130 offset1:195
	s_waitcnt lgkmcnt(0)
	v_cvt_pk_bf16_f32 v3, v4, v5
	ds_read2_b32 v[4:5], v68 offset0:4 offset1:69
	s_waitcnt lgkmcnt(0)
	v_cvt_pk_bf16_f32 v4, v4, v5
	ds_read2_b32 v[6:7], v68 offset0:134 offset1:199
	s_lshl_b64 s[0:1], s[8:9], 1
	s_add_u32 s0, s34, s0
	s_waitcnt lgkmcnt(0)
	v_cvt_pk_bf16_f32 v5, v6, v7
	v_or_b32_e32 v6, s6, v105
	s_addc_u32 s1, s37, s1
	v_ashrrev_i32_e32 v7, 31, v6
	v_lshl_add_u64 v[8:9], s[0:1], 0, v[66:67]
	v_lshlrev_b64 v[6:7], 12, v[6:7]
	v_lshl_add_u64 v[6:7], v[8:9], 0, v[6:7]
	ds_read2_b32 v[10:11], v1 offset0:8 offset1:73
	global_store_dwordx4 v[6:7], v[2:5], off sc0 sc1
	s_waitcnt lgkmcnt(0)
	s_nop 0
	v_cvt_pk_bf16_f32 v2, v10, v11
	ds_read2_b32 v[4:5], v1 offset0:138 offset1:203
	s_waitcnt lgkmcnt(0)
	v_cvt_pk_bf16_f32 v3, v4, v5
	ds_read2_b32 v[4:5], v68 offset0:12 offset1:77
	s_waitcnt lgkmcnt(0)
	v_cvt_pk_bf16_f32 v4, v4, v5
	ds_read2_b32 v[6:7], v68 offset0:142 offset1:207
	s_waitcnt lgkmcnt(0)
	v_cvt_pk_bf16_f32 v5, v6, v7
	v_or_b32_e32 v6, s6, v69
	v_ashrrev_i32_e32 v7, 31, v6
	v_lshlrev_b64 v[6:7], 12, v[6:7]
	v_lshl_add_u64 v[6:7], v[8:9], 0, v[6:7]
	ds_read2_b32 v[10:11], v1 offset0:16 offset1:81
	global_store_dwordx4 v[6:7], v[2:5], off sc0 sc1
	s_waitcnt lgkmcnt(0)
	s_nop 0
	v_cvt_pk_bf16_f32 v2, v10, v11
	ds_read2_b32 v[4:5], v1 offset0:146 offset1:211
	s_waitcnt lgkmcnt(0)
	v_cvt_pk_bf16_f32 v3, v4, v5
	ds_read2_b32 v[4:5], v68 offset0:20 offset1:85
	s_waitcnt lgkmcnt(0)
	v_cvt_pk_bf16_f32 v4, v4, v5
	ds_read2_b32 v[6:7], v68 offset0:150 offset1:215
	s_waitcnt lgkmcnt(0)
	v_cvt_pk_bf16_f32 v5, v6, v7
	v_or_b32_e32 v6, s6, v106
	v_ashrrev_i32_e32 v7, 31, v6
	v_lshlrev_b64 v[6:7], 12, v[6:7]
	v_lshl_add_u64 v[6:7], v[8:9], 0, v[6:7]
	ds_read2_b32 v[10:11], v1 offset0:24 offset1:89
	global_store_dwordx4 v[6:7], v[2:5], off sc0 sc1
	s_waitcnt lgkmcnt(0)
	s_nop 0
	v_cvt_pk_bf16_f32 v2, v10, v11
	ds_read2_b32 v[4:5], v1 offset0:154 offset1:219
	s_waitcnt lgkmcnt(0)
	v_cvt_pk_bf16_f32 v3, v4, v5
	ds_read2_b32 v[4:5], v68 offset0:28 offset1:93
	s_waitcnt lgkmcnt(0)
	v_cvt_pk_bf16_f32 v4, v4, v5
	ds_read2_b32 v[6:7], v68 offset0:158 offset1:223
	s_waitcnt lgkmcnt(0)
	v_cvt_pk_bf16_f32 v5, v6, v7
	v_or_b32_e32 v6, s6, v107
	v_ashrrev_i32_e32 v7, 31, v6
	v_lshlrev_b64 v[6:7], 12, v[6:7]
	v_lshl_add_u64 v[6:7], v[8:9], 0, v[6:7]
	ds_read2_b32 v[10:11], v1 offset0:32 offset1:97
	global_store_dwordx4 v[6:7], v[2:5], off sc0 sc1
	s_waitcnt lgkmcnt(0)
	s_nop 0
	v_cvt_pk_bf16_f32 v2, v10, v11
	ds_read2_b32 v[4:5], v1 offset0:162 offset1:227
	s_waitcnt lgkmcnt(0)
	v_cvt_pk_bf16_f32 v3, v4, v5
	ds_read2_b32 v[4:5], v68 offset0:36 offset1:101
	s_waitcnt lgkmcnt(0)
	v_cvt_pk_bf16_f32 v4, v4, v5
	ds_read2_b32 v[6:7], v68 offset0:166 offset1:231
	s_waitcnt lgkmcnt(0)
	v_cvt_pk_bf16_f32 v5, v6, v7
	v_or_b32_e32 v6, s6, v108
	v_ashrrev_i32_e32 v7, 31, v6
	v_lshlrev_b64 v[6:7], 12, v[6:7]
	v_lshl_add_u64 v[6:7], v[8:9], 0, v[6:7]
	ds_read2_b32 v[10:11], v1 offset0:40 offset1:105
	global_store_dwordx4 v[6:7], v[2:5], off sc0 sc1
	s_waitcnt lgkmcnt(0)
	s_nop 0
	v_cvt_pk_bf16_f32 v2, v10, v11
	ds_read2_b32 v[4:5], v1 offset0:170 offset1:235
	s_waitcnt lgkmcnt(0)
	v_cvt_pk_bf16_f32 v3, v4, v5
	ds_read2_b32 v[4:5], v68 offset0:44 offset1:109
	s_waitcnt lgkmcnt(0)
	v_cvt_pk_bf16_f32 v4, v4, v5
	ds_read2_b32 v[6:7], v68 offset0:174 offset1:239
	s_waitcnt lgkmcnt(0)
	v_cvt_pk_bf16_f32 v5, v6, v7
	v_or_b32_e32 v6, s6, v109
	v_ashrrev_i32_e32 v7, 31, v6
	v_lshlrev_b64 v[6:7], 12, v[6:7]
	v_lshl_add_u64 v[6:7], v[8:9], 0, v[6:7]
	ds_read2_b32 v[10:11], v1 offset0:48 offset1:113
	global_store_dwordx4 v[6:7], v[2:5], off sc0 sc1
	s_waitcnt lgkmcnt(0)
	s_nop 0
	v_cvt_pk_bf16_f32 v2, v10, v11
	ds_read2_b32 v[4:5], v1 offset0:178 offset1:243
	s_waitcnt lgkmcnt(0)
	v_cvt_pk_bf16_f32 v3, v4, v5
	ds_read2_b32 v[4:5], v68 offset0:52 offset1:117
	s_waitcnt lgkmcnt(0)
	v_cvt_pk_bf16_f32 v4, v4, v5
	ds_read2_b32 v[6:7], v68 offset0:182 offset1:247
	s_waitcnt lgkmcnt(0)
	v_cvt_pk_bf16_f32 v5, v6, v7
	v_or_b32_e32 v6, s6, v110
	v_ashrrev_i32_e32 v7, 31, v6
	v_lshlrev_b64 v[6:7], 12, v[6:7]
	v_lshl_add_u64 v[6:7], v[8:9], 0, v[6:7]
	ds_read2_b32 v[10:11], v1 offset0:56 offset1:121
	global_store_dwordx4 v[6:7], v[2:5], off sc0 sc1
	s_waitcnt lgkmcnt(0)
	s_nop 0
	v_cvt_pk_bf16_f32 v2, v10, v11
	ds_read2_b32 v[4:5], v1 offset0:186 offset1:251
	s_waitcnt lgkmcnt(0)
	v_cvt_pk_bf16_f32 v3, v4, v5
	ds_read2_b32 v[4:5], v68 offset0:60 offset1:125
	s_waitcnt lgkmcnt(0)
	v_cvt_pk_bf16_f32 v4, v4, v5
	ds_read2_b32 v[6:7], v68 offset0:190 offset1:255
	s_waitcnt lgkmcnt(0)
	v_cvt_pk_bf16_f32 v5, v6, v7
	v_or_b32_e32 v6, s6, v78
	v_ashrrev_i32_e32 v7, 31, v6
	v_lshlrev_b64 v[6:7], 12, v[6:7]
	v_lshl_add_u64 v[6:7], v[8:9], 0, v[6:7]
	global_store_dwordx4 v[6:7], v[2:5], off sc0 sc1
	s_waitcnt lgkmcnt(0)
